# EpiUp row-scale: 8 serialized SS loads + 14 bpermute hops batched into one load round + two permute rounds
# speedup vs baseline: 1.2887x; 1.0055x over previous
; #define A (*args_opaque((CArgs*)__builtin_amdgcn_kernarg_segment_ptr()))
;     __device__ __forceinline__ void operator()(f32x4 (&acc)[2][2][4][2], const pg8::Unit& u, int wr, int wc, int fr, int fq) const {
;     ...
;         for (int ai = 0; ai < 2; ++ai)
; #pragma unroll
;             for (int m = 0; m < 4; ++m) { const size_t row = (size_t)pm * 256 + ai * 128 + wr * 64 + m * 16 + fr;
;                 float s;
;                 if (sample) { s = 256.f; if (ai == 0) { const f32x4* sq = (const f32x4*)((const float*)(A.ws + WS_SSS) + (row - MPR) * 64 + 16 * fq); s = 0.f;
; #pragma unroll
;                     for (int k = 0; k < 4; ++k) { const f32x4 q = sq[k]; s += (q.x + q.y) + (q.z + q.w); } } }
;                 else { const f32x4 a = *(const f32x4*)(SS + row * 16 + 4 * fq); s = (a.x + a.y) + (a.z + a.w); }
;                 s += __shfl_xor(s, 16); s += __shfl_xor(s, 32);
;                 const float rs = rsqrtf(s * (1.f / 1024.f) + EPSF);
.LBB0_1211:
	v_ashrrev_i32_e32 v197, 31, v196
	s_waitcnt lgkmcnt(0)
	v_lshl_add_u64 v[196:197], v[196:197], 2, s[54:55]
	s_mov_b64 s[46:47], 0x5f00000
	v_lshl_add_u64 v[200:201], v[196:197], 0, s[46:47]
	v_lshlrev_b64 v[196:197], 6, v[218:219]
	s_andn2_b64 vcc, exec, s[22:23]
	v_lshl_add_u64 v[196:197], v[200:201], 0, v[196:197]
	s_cbranch_vccnz .LBB0_1213
	v_and_b32_e32 v3, 64, v232
	v_xor_b32_e32 v1, 16, v232
	v_add_u32_e32 v3, 64, v3
	v_cmp_lt_i32_e32 vcc, v1, v3
	v_xor_b32_e32 v217, 32, v232
	s_nop 1
	v_cndmask_b32_e32 v1, v232, v1, vcc
	v_cmp_lt_i32_e32 vcc, v217, v3
	v_lshlrev_b32_e32 v1, 2, v1
	s_nop 0
	v_cndmask_b32_e32 v3, v232, v217, vcc
	v_lshlrev_b32_e32 v3, 2, v3
	global_load_dwordx4 v[220:223], v[196:197], off
	global_load_dwordx4 v[224:227], v[196:197], off offset:1024
	global_load_dwordx4 v[228:231], v[196:197], off offset:2048
	global_load_dwordx4 v[198:201], v[196:197], off offset:3072
	v_add_co_u32_e32 v196, vcc, 0x2000, v196
	s_nop 1
	v_addc_co_u32_e32 v197, vcc, 0, v197, vcc
	global_load_dwordx4 v[244:247], v[196:197], off
	global_load_dwordx4 v[240:243], v[196:197], off offset:1024
	global_load_dwordx4 v[248:251], v[196:197], off offset:2048
	global_load_dwordx2 v[202:203], v[196:197], off offset:3072
	global_load_dwordx2 v[252:253], v[196:197], off offset:3080
	s_waitcnt vmcnt(0)
	v_add_f32_e32 v220, v220, v221
	v_add_f32_e32 v222, v222, v223
	v_add_f32_e32 v224, v224, v225
	v_add_f32_e32 v226, v226, v227
	v_add_f32_e32 v228, v228, v229
	v_add_f32_e32 v230, v230, v231
	v_add_f32_e32 v198, v198, v199
	v_add_f32_e32 v200, v200, v201
	v_add_f32_e32 v244, v244, v245
	v_add_f32_e32 v246, v246, v247
	v_add_f32_e32 v240, v240, v241
	v_add_f32_e32 v242, v242, v243
	v_add_f32_e32 v248, v248, v249
	v_add_f32_e32 v250, v250, v251
	v_add_f32_e32 v202, v202, v203
	v_add_f32_e32 v252, v252, v253
	v_add_f32_e32 v220, v220, v222
	v_add_f32_e32 v224, v224, v226
	v_add_f32_e32 v228, v228, v230
	v_add_f32_e32 v198, v198, v200
	v_add_f32_e32 v244, v244, v246
	v_add_f32_e32 v240, v240, v242
	v_add_f32_e32 v248, v248, v250
	v_add_f32_e32 v200, v202, v252
	ds_bpermute_b32 v221, v1, v220
	ds_bpermute_b32 v225, v1, v224
	ds_bpermute_b32 v229, v1, v228
	ds_bpermute_b32 v199, v1, v198
	ds_bpermute_b32 v247, v1, v244
	ds_bpermute_b32 v241, v1, v240
	ds_bpermute_b32 v249, v1, v248
	s_waitcnt lgkmcnt(0)
	v_add_f32_e32 v217, v220, v221
	v_add_f32_e32 v221, v224, v225
	v_add_f32_e32 v223, v228, v229
	v_add_f32_e32 v198, v198, v199
	v_add_f32_e32 v245, v244, v247
	v_add_f32_e32 v240, v240, v241
	v_add_f32_e32 v243, v248, v249
	ds_bpermute_b32 v220, v3, v217
	ds_bpermute_b32 v222, v3, v221
	ds_bpermute_b32 v224, v3, v223
	ds_bpermute_b32 v199, v3, v198
	ds_bpermute_b32 v246, v3, v245
	ds_bpermute_b32 v241, v3, v240
	ds_bpermute_b32 v244, v3, v243
	s_waitcnt lgkmcnt(0)
	s_branch .LBB0_1233
